# attention loop: first QK MFMA waits for five K fragments instead of six
# baseline (speedup 1.0000x reference)
; #define LAS __attribute__((address_space(3)))
; DI f32x16 mfma32(bf16x8 a, bf16x8 b, f32x16 c) { return __builtin_amdgcn_mfma_f32_32x32x16_bf16(a, b, c, 0, 0, 0); }
; template <int VAR> DI void phase_attn(LAS unsigned char* lds, const bf16_t* Q, const bf16_t* K, const bf16_t* VT, bf16_t* O) {
;     ...
;             if (VAR != 4 && j <= my_last) {
;                 LAS const unsigned char* kb = kbuf + buf * KBUF + r32 * KPITCH + 16 * hi; LAS const unsigned char* vb = vbuf + buf * VBUF + r32 * VPITCH + 16 * hi;
;                 f32x16 p0, p1;
; #pragma unroll
;                 for (int r = 0; r < 16; ++r) { p0[r] = -mrun; p1[r] = -mrun; }
;                 bf16x8 ka[12], va[8];
; #pragma unroll
;                 for (int s = 0; s < 6; ++s) { ka[2 * s] = *(LAS const bf16x8*)(kb + 32 * s); ka[2 * s + 1] = *(LAS const bf16x8*)(kb + 32 * KPITCH + 32 * s); }
; #pragma unroll
;                 for (int f = 0; f < 4; ++f) { va[2 * f] = *(LAS const bf16x8*)(vb + 32 * f); va[2 * f + 1] = *(LAS const bf16x8*)(vb + 32 * VPITCH + 32 * f); }
;                 __builtin_amdgcn_sched_barrier(0);
; #pragma unroll
;                 for (int s = 0; s < 6; ++s) { if (VAR == 2) { p0[s] += __builtin_bit_cast(f32x4, ka[2 * s])[0]; p1[s] += __builtin_bit_cast(f32x4, ka[2 * s + 1])[1]; } else { p0 = mfma32(ka[2 * s], qr[s], p0); p1 = mfma32(ka[2 * s + 1], qr[s], p1); } }
;                 if (64 * j + 63 > qw0) {
;                     const int qa = qw0 + r32, kb0 = 64 * j + 4 * hi;
; #pragma unroll
;                     for (int r = 0; r < 16; ++r) { const int kv = kb0 + (r & 3) + 8 * (r >> 2); if (kv > qa) p0[r] = -INFINITY; if (kv + 32 > qa) p1[r] = -INFINITY; }
;                 }
.LBB0_70:
	s_mul_i32 s9, s8, 0x3400
	v_add_u32_e32 v44, s9, v169
	ds_read_b128 v[208:211], v44
	ds_read_b128 v[212:215], v44 offset:32
	ds_read_b128 v[216:219], v44 offset:6656
	ds_read_b128 v[220:223], v44 offset:6688
	ds_read_b128 v[224:227], v44 offset:64
	ds_read_b128 v[228:231], v44 offset:96
	ds_read_b128 v[232:235], v44 offset:6720
	ds_read_b128 v[236:239], v44 offset:6752
	ds_read_b128 v[240:243], v44 offset:128
	ds_read_b128 v[244:247], v44 offset:160
	ds_read_b128 v[248:251], v44 offset:6784
	ds_read_b128 v[172:175], v44 offset:6816
	s_mul_i32 s43, s8, 0x2400
	v_add_u32_e32 v44, s43, v170
	ds_read_b128 v[130:133], v44 offset:26624
	ds_read_b128 v[122:125], v44 offset:26656
	ds_read_b128 v[126:129], v44 offset:31232
	ds_read_b128 v[118:121], v44 offset:31264
	ds_read_b128 v[114:117], v44 offset:26688
	ds_read_b128 v[106:109], v44 offset:26720
	ds_read_b128 v[110:113], v44 offset:31296
	ds_read_b128 v[102:105], v44 offset:31328
	s_waitcnt lgkmcnt(15)
	s_nop 0
	v_mfma_f32_32x32x16_bf16 v[48:63], v[208:211], v[66:69], v[176:191]
	s_add_i32 s9, s98, -1
	s_cmp_le_i32 s9, s36
	v_mfma_f32_32x32x16_bf16 v[32:47], v[216:219], v[66:69], v[176:191]
	v_mfma_f32_32x32x16_bf16 v[48:63], v[212:215], v[70:73], v[48:63]
	v_mfma_f32_32x32x16_bf16 v[32:47], v[220:223], v[70:73], v[32:47]
	v_mfma_f32_32x32x16_bf16 v[48:63], v[224:227], v[74:77], v[48:63]
	s_waitcnt lgkmcnt(13)
	v_mfma_f32_32x32x16_bf16 v[32:47], v[232:235], v[74:77], v[32:47]
	v_mfma_f32_32x32x16_bf16 v[48:63], v[228:231], v[78:81], v[48:63]
	s_waitcnt lgkmcnt(12)
	v_mfma_f32_32x32x16_bf16 v[32:47], v[236:239], v[78:81], v[32:47]
	s_waitcnt lgkmcnt(11)
	v_mfma_f32_32x32x16_bf16 v[48:63], v[240:243], v[82:85], v[48:63]
	s_waitcnt lgkmcnt(9)
	v_mfma_f32_32x32x16_bf16 v[32:47], v[248:251], v[82:85], v[32:47]
	v_mfma_f32_32x32x16_bf16 v[48:63], v[244:247], v[86:89], v[48:63]
	s_waitcnt lgkmcnt(8)
	v_mfma_f32_32x32x16_bf16 v[32:47], v[172:175], v[86:89], v[32:47]
	s_cbranch_scc1 .LBB0_72
	v_add_u32_e32 v172, s98, v144
	v_subrev_u32_e32 v174, 32, v172
	v_subrev_u32_e32 v173, 64, v172
	v_cmp_le_i32_e32 vcc, v174, v201
	s_nop 6
	v_cndmask_b32_e32 v32, v167, v32, vcc
	v_cmp_lt_i32_e32 vcc, v173, v201
	s_nop 1
	v_cndmask_b32_e32 v49, v167, v49, vcc
	v_cmp_le_i32_e32 vcc, v173, v201
	v_subrev_u32_e32 v173, 31, v172
	s_nop 0
	v_cndmask_b32_e32 v48, v167, v48, vcc
	v_cmp_le_i32_e32 vcc, v173, v201
	v_subrev_u32_e32 v173, 62, v172
	s_nop 0
	v_cndmask_b32_e32 v33, v167, v33, vcc
	v_cmp_le_i32_e32 vcc, v173, v201
	v_subrev_u32_e32 v173, 30, v172
	s_nop 0
	v_cndmask_b32_e32 v50, v167, v50, vcc
	v_cmp_le_i32_e32 vcc, v173, v201
	v_subrev_u32_e32 v173, 61, v172
	s_nop 0
	v_cndmask_b32_e32 v34, v167, v34, vcc
	v_cmp_le_i32_e32 vcc, v173, v201
	v_subrev_u32_e32 v173, 29, v172
	s_nop 0
	v_cndmask_b32_e32 v51, v167, v51, vcc
	v_cmp_le_i32_e32 vcc, v173, v201
	v_subrev_u32_e32 v173, 56, v172
	s_nop 0
	v_cndmask_b32_e32 v35, v167, v35, vcc
	v_cmp_le_i32_e32 vcc, v173, v201
	v_subrev_u32_e32 v173, 24, v172
	s_nop 0
	v_cndmask_b32_e32 v52, v167, v52, vcc
	v_cmp_le_i32_e32 vcc, v173, v201
	v_subrev_u32_e32 v173, 55, v172
	s_nop 0
	v_cndmask_b32_e32 v36, v167, v36, vcc
	v_cmp_le_i32_e32 vcc, v173, v201
	v_subrev_u32_e32 v173, 23, v172
	s_nop 0
	v_cndmask_b32_e32 v53, v167, v53, vcc
	v_cmp_le_i32_e32 vcc, v173, v201
	v_subrev_u32_e32 v173, 54, v172
	s_nop 0
	v_cndmask_b32_e32 v37, v167, v37, vcc
	v_cmp_le_i32_e32 vcc, v173, v201
	v_subrev_u32_e32 v173, 22, v172
	s_nop 0
	v_cndmask_b32_e32 v54, v167, v54, vcc
	v_cmp_le_i32_e32 vcc, v173, v201
	v_subrev_u32_e32 v173, 53, v172
	s_nop 0
	v_cndmask_b32_e32 v38, v167, v38, vcc
	v_cmp_le_i32_e32 vcc, v173, v201
	v_subrev_u32_e32 v173, 21, v172
	s_nop 0
	v_cndmask_b32_e32 v55, v167, v55, vcc
	v_cmp_le_i32_e32 vcc, v173, v201
	v_subrev_u32_e32 v173, 48, v172
	s_nop 0
	v_cndmask_b32_e32 v39, v167, v39, vcc
	v_cmp_le_i32_e32 vcc, v173, v201
	v_add_u32_e32 v173, -16, v172
	s_nop 0
	v_cndmask_b32_e32 v56, v167, v56, vcc
	v_cmp_le_i32_e32 vcc, v173, v201
	v_subrev_u32_e32 v173, 47, v172
	s_nop 0
	v_cndmask_b32_e32 v40, v167, v40, vcc
	v_cmp_le_i32_e32 vcc, v173, v201
	v_add_u32_e32 v173, -15, v172
	s_nop 0
	v_cndmask_b32_e32 v57, v167, v57, vcc
	v_cmp_le_i32_e32 vcc, v173, v201
	v_subrev_u32_e32 v173, 46, v172
	s_nop 0
	v_cndmask_b32_e32 v41, v167, v41, vcc
	v_cmp_le_i32_e32 vcc, v173, v201
	v_add_u32_e32 v173, -14, v172
	s_nop 0
	v_cndmask_b32_e32 v58, v167, v58, vcc
	v_cmp_le_i32_e32 vcc, v173, v201
	v_subrev_u32_e32 v173, 45, v172
	s_nop 0
	v_cndmask_b32_e32 v42, v167, v42, vcc
	v_cmp_le_i32_e32 vcc, v173, v201
	v_add_u32_e32 v173, -13, v172
	s_nop 0
	v_cndmask_b32_e32 v59, v167, v59, vcc
	v_cmp_le_i32_e32 vcc, v173, v201
	v_subrev_u32_e32 v173, 40, v172
	s_nop 0
	v_cndmask_b32_e32 v43, v167, v43, vcc
	v_cmp_le_i32_e32 vcc, v173, v201
	v_add_u32_e32 v173, -8, v172
	s_nop 0
	v_cndmask_b32_e32 v60, v167, v60, vcc
	v_cmp_le_i32_e32 vcc, v173, v201
	v_subrev_u32_e32 v173, 39, v172
	s_nop 0
	v_cndmask_b32_e32 v44, v167, v44, vcc
	v_cmp_le_i32_e32 vcc, v173, v201
	v_add_u32_e32 v173, -7, v172
	s_nop 0
	v_cndmask_b32_e32 v61, v167, v61, vcc
	v_cmp_le_i32_e32 vcc, v173, v201
	v_subrev_u32_e32 v173, 38, v172
	s_nop 0
	v_cndmask_b32_e32 v45, v167, v45, vcc
	v_cmp_le_i32_e32 vcc, v173, v201
	v_add_u32_e32 v173, -6, v172
	s_nop 0
	v_cndmask_b32_e32 v62, v167, v62, vcc
	v_cmp_le_i32_e32 vcc, v173, v201
	v_subrev_u32_e32 v173, 37, v172
	v_add_u32_e32 v172, -5, v172
	v_cndmask_b32_e32 v46, v167, v46, vcc
	v_cmp_le_i32_e32 vcc, v173, v201
	s_nop 1
	v_cndmask_b32_e32 v63, v167, v63, vcc
	v_cmp_le_i32_e32 vcc, v172, v201
	s_nop 1
	v_cndmask_b32_e32 v47, v167, v47, vcc
